# merge epilogue: 16-byte write-through stores via v_permlane32_swap pairing (on top of v32 stack)
# baseline (speedup 1.0000x reference)
.LBB0_1851:
	s_or_b64 exec, exec, s[0:1]
	v_readlane_b32 s0, v254, 12
	v_readlane_b32 s1, v254, 13
	s_andn2_b64 vcc, exec, s[0:1]
	s_waitcnt lgkmcnt(0)
	s_barrier
	s_cbranch_vccnz .LBB0_1914
	s_getreg_b32 s0, hwreg(HW_REG_HW_ID, 0, 6)
	s_lshl_b32 s0, s0, 2
	s_and_b32 s0, s0, 0xfc
	s_add_i32 s0, s0, 0x24800
	v_mov_b32_e32 v0, s0
	ds_read_b32 v0, v0
	v_mov_b32_e32 v220, 0x244d8
	ds_read2_b32 v[222:223], v220 offset1:1
	ds_read2_b32 v[224:225], v220 offset0:2 offset1:3
	v_mbcnt_lo_u32_b32 v221, -1, 0
	v_mbcnt_hi_u32_b32 v221, -1, v221
	s_waitcnt lgkmcnt(0)
	v_readfirstlane_b32 s38, v0
	v_readfirstlane_b32 s46, v222
	v_readfirstlane_b32 s47, v223
	v_readfirstlane_b32 s2, v224
	v_readfirstlane_b32 s3, v225
	v_readlane_b32 s40, v254, 55
	v_readlane_b32 s41, v254, 56
	v_readlane_b32 s24, v254, 11
	s_lshl_b32 s22, s38, 12
	s_lshl_b32 s25, s38, 11
	s_add_i32 s25, s25, 0x8000
	s_lshr_b32 s0, s38, 1
	s_and_b32 s1, s38, 1
	s_lshl_b32 s39, s0, 13
	s_lshl_b32 s30, s1, 13
	s_add_i32 s30, s30, 0x8000
	v_and_b32_e32 v220, 31, v221
	v_lshrrev_b32_e32 v222, 5, v221
	v_bfe_u32 v223, v221, 1, 3
	v_xor_b32_e32 v223, v223, v222
	v_lshlrev_b32_e32 v224, 7, v220
	v_lshl_or_b32 v225, v223, 4, v224
	v_add_u32_e32 v210, s39, v225
	v_add_u32_e32 v214, s30, v225
	v_xor_b32_e32 v226, 2, v223
	v_lshl_or_b32 v225, v226, 4, v224
	v_add_u32_e32 v211, s39, v225
	v_add_u32_e32 v215, s30, v225
	v_xor_b32_e32 v226, 4, v223
	v_lshl_or_b32 v225, v226, 4, v224
	v_add_u32_e32 v212, s39, v225
	v_add_u32_e32 v216, s30, v225
	v_xor_b32_e32 v226, 6, v223
	v_lshl_or_b32 v225, v226, 4, v224
	v_add_u32_e32 v213, s39, v225
	v_add_u32_e32 v217, s30, v225
	s_lshl_b32 s31, s0, 12
	v_lshlrev_b32_e32 v225, 6, v220
	v_add_u32_e32 v180, s31, v225
	s_lshl_b32 s31, s0, 17
	s_lshl_b32 s0, s1, 7
	s_add_i32 s31, s31, s0
	v_lshlrev_b32_e32 v225, 11, v220
	v_lshl_or_b32 v225, v222, 4, v225
	v_add_u32_e32 v178, s31, v225
	v_add_u32_e32 v179, 0x10000, v178
	v_and_b32_e32 v222, 7, v221
	v_bfe_u32 v223, v221, 4, 2
	v_xor_b32_e32 v222, v222, v223
	v_lshrrev_b32_e32 v223, 3, v221
	v_lshlrev_b32_e32 v224, 11, v223
	v_lshl_or_b32 v224, v222, 4, v224
	v_lshlrev_b32_e32 v225, 9, v223
	v_lshl_or_b32 v225, v222, 4, v225
	s_lshl_b32 s0, s38, 16
	s_add_i32 s1, s0, 0x0
	v_add_u32_e32 v202, s1, v224
	s_add_i32 s1, s0, 0x4000
	v_add_u32_e32 v203, s1, v224
	v_xor_b32_e32 v203, 64, v203
	s_add_i32 s1, s0, 0x8000
	v_add_u32_e32 v204, s1, v224
	s_add_i32 s1, s0, 0xc000
	v_add_u32_e32 v205, s1, v224
	v_xor_b32_e32 v205, 64, v205
	s_lshl_b32 s0, s38, 15
	s_add_i32 s1, s0, 0x0
	v_add_u32_e32 v206, s1, v224
	s_add_i32 s1, s0, 0x4000
	v_add_u32_e32 v207, s1, v224
	v_xor_b32_e32 v207, 64, v207
	s_lshl_b32 s0, s38, 13
	s_add_i32 s1, s0, 0x0
	v_add_u32_e32 v208, s1, v225
	s_add_i32 s1, s0, 0x1000
	v_add_u32_e32 v209, s1, v225
	v_xor_b32_e32 v209, 64, v209
	s_mov_b32 s21, 0

.Lmg_gloop:
	s_waitcnt vmcnt(6)
	s_barrier
	ds_read_b128 v[186:189], v214
	ds_read_b128 v[194:197], v210
	ds_read_b128 v[198:201], v210 offset:4096
	ds_read_b128 v[190:193], v214 offset:4096
	s_add_i32 s28, s20, s22
	s_add_i32 s29, s20, s25
	s_add_i32 m0, s28, 0x0
	v_mfma_f32_32x32x16_f16 v[2:17], v[162:165], v[170:173], v[2:17]
	global_load_lds_dwordx4 v202, s[12:13]
	s_add_i32 m0, s28, 0x400
	v_mfma_f32_32x32x16_f16 v[18:33], v[162:165], v[174:177], v[18:33]
	global_load_lds_dwordx4 v203, s[12:13]
	s_add_i32 m0, s28, 0x800
	v_mfma_f32_32x32x16_f16 v[34:49], v[166:169], v[170:173], v[34:49]
	global_load_lds_dwordx4 v204, s[12:13]
	s_add_i32 m0, s28, 0xc00
	v_mfma_f32_32x32x16_f16 v[50:65], v[166:169], v[174:177], v[50:65]
	global_load_lds_dwordx4 v205, s[12:13]
	ds_read_b128 v[162:165], v215
	ds_read_b128 v[170:173], v211
	ds_read_b128 v[174:177], v211 offset:4096
	ds_read_b128 v[166:169], v215 offset:4096
	s_waitcnt lgkmcnt(6)
	s_add_i32 m0, s29, 0x0
	v_mfma_f32_32x32x16_f16 v[2:17], v[186:189], v[194:197], v[2:17]
	global_load_lds_dwordx4 v206, s[14:15]
	s_waitcnt lgkmcnt(5)
	s_add_i32 m0, s29, 0x400
	v_mfma_f32_32x32x16_f16 v[18:33], v[186:189], v[198:201], v[18:33]
	global_load_lds_dwordx4 v207, s[14:15]
	s_waitcnt lgkmcnt(4)
	v_mfma_f32_32x32x16_f16 v[34:49], v[190:193], v[194:197], v[34:49]
	s_add_u32 s12, s12, 0x80
	s_addc_u32 s13, s13, 0
	v_mfma_f32_32x32x16_f16 v[50:65], v[190:193], v[198:201], v[50:65]
	s_add_u32 s14, s14, 0x80
	s_addc_u32 s15, s15, 0
	ds_read_b128 v[186:189], v216
	ds_read_b128 v[194:197], v212
	ds_read_b128 v[198:201], v212 offset:4096
	ds_read_b128 v[190:193], v216 offset:4096
	s_add_i32 s20, s20, 0xc000
	s_cmp_eq_u32 s20, 0x24000
	s_cselect_b32 s20, 0, s20
	s_waitcnt lgkmcnt(6)
	v_mfma_f32_32x32x16_f16 v[2:17], v[162:165], v[170:173], v[2:17]
	s_add_i32 s30, s21, 0xc000
	s_waitcnt lgkmcnt(5)
	v_mfma_f32_32x32x16_f16 v[18:33], v[162:165], v[174:177], v[18:33]
	s_cmp_eq_u32 s30, 0x24000
	s_waitcnt lgkmcnt(4)
	v_mfma_f32_32x32x16_f16 v[34:49], v[166:169], v[170:173], v[34:49]
	s_cselect_b32 s30, 0, s30
	v_mfma_f32_32x32x16_f16 v[50:65], v[166:169], v[174:177], v[50:65]
	s_sub_i32 s23, s30, s21
	s_mov_b32 s21, s30
	ds_read_b128 v[162:165], v217
	ds_read_b128 v[170:173], v213
	ds_read_b128 v[174:177], v213 offset:4096
	ds_read_b128 v[166:169], v217 offset:4096
	s_waitcnt lgkmcnt(6)
	v_mfma_f32_32x32x16_f16 v[2:17], v[186:189], v[194:197], v[2:17]
	v_add_u32_e32 v210, s23, v210
	v_add_u32_e32 v214, s23, v214
	s_waitcnt lgkmcnt(5)
	v_mfma_f32_32x32x16_f16 v[18:33], v[186:189], v[198:201], v[18:33]
	v_add_u32_e32 v211, s23, v211
	v_add_u32_e32 v215, s23, v215
	s_waitcnt lgkmcnt(4)
	v_mfma_f32_32x32x16_f16 v[34:49], v[190:193], v[194:197], v[34:49]
	v_add_u32_e32 v212, s23, v212
	v_add_u32_e32 v216, s23, v216
	v_mfma_f32_32x32x16_f16 v[50:65], v[190:193], v[198:201], v[50:65]
	v_add_u32_e32 v213, s23, v213
	v_add_u32_e32 v217, s23, v217
	s_waitcnt lgkmcnt(0)
	s_sub_i32 s27, s27, 1
	s_cmp_lg_u32 s27, 0
	s_cbranch_scc1 .Lmg_gloop
	s_waitcnt vmcnt(6)
	s_barrier
	ds_read_b128 v[186:189], v214
	ds_read_b128 v[194:197], v210
	ds_read_b128 v[198:201], v210 offset:4096
	ds_read_b128 v[190:193], v214 offset:4096
	s_add_i32 s28, s20, s22
	s_add_i32 s29, s20, s25
	s_add_i32 m0, s28, 0x0
	v_mfma_f32_32x32x16_f16 v[2:17], v[162:165], v[170:173], v[2:17]
	global_load_lds_dwordx4 v202, s[16:17]
	s_add_i32 m0, s28, 0x400
	v_mfma_f32_32x32x16_f16 v[18:33], v[162:165], v[174:177], v[18:33]
	global_load_lds_dwordx4 v203, s[16:17]
	s_add_i32 m0, s28, 0x800
	v_mfma_f32_32x32x16_f16 v[34:49], v[166:169], v[170:173], v[34:49]
	global_load_lds_dwordx4 v204, s[16:17]
	s_add_i32 m0, s28, 0xc00
	v_mfma_f32_32x32x16_f16 v[50:65], v[166:169], v[174:177], v[50:65]
	global_load_lds_dwordx4 v205, s[16:17]
	ds_read_b128 v[162:165], v215
	ds_read_b128 v[170:173], v211
	ds_read_b128 v[174:177], v211 offset:4096
	ds_read_b128 v[166:169], v215 offset:4096
	s_waitcnt lgkmcnt(6)
	s_add_i32 m0, s29, 0x0
	v_mfma_f32_32x32x16_f16 v[2:17], v[186:189], v[194:197], v[2:17]
	global_load_lds_dwordx4 v208, s[18:19]
	s_waitcnt lgkmcnt(5)
	s_add_i32 m0, s29, 0x400
	v_mfma_f32_32x32x16_f16 v[18:33], v[186:189], v[198:201], v[18:33]
	global_load_lds_dwordx4 v209, s[18:19]
	s_waitcnt lgkmcnt(4)
	v_mfma_f32_32x32x16_f16 v[34:49], v[190:193], v[194:197], v[34:49]
	s_add_u32 s16, s16, 0x80
	s_addc_u32 s17, s17, 0
	v_mfma_f32_32x32x16_f16 v[50:65], v[190:193], v[198:201], v[50:65]
	s_add_u32 s18, s18, 0x80
	s_addc_u32 s19, s19, 0
	ds_read_b128 v[186:189], v216
	ds_read_b128 v[194:197], v212
	ds_read_b128 v[198:201], v212 offset:4096
	ds_read_b128 v[190:193], v216 offset:4096
	s_add_i32 s20, s20, 0xc000
	s_cmp_eq_u32 s20, 0x24000
	s_cselect_b32 s20, 0, s20
	s_waitcnt lgkmcnt(6)
	v_mfma_f32_32x32x16_f16 v[2:17], v[162:165], v[170:173], v[2:17]
	s_add_i32 s30, s21, 0xc000
	s_waitcnt lgkmcnt(5)
	v_mfma_f32_32x32x16_f16 v[18:33], v[162:165], v[174:177], v[18:33]
	s_cmp_eq_u32 s30, 0x24000
	s_waitcnt lgkmcnt(4)
	v_mfma_f32_32x32x16_f16 v[34:49], v[166:169], v[170:173], v[34:49]
	s_cselect_b32 s30, 0, s30
	v_mfma_f32_32x32x16_f16 v[50:65], v[166:169], v[174:177], v[50:65]
	s_sub_i32 s23, s30, s21
	s_mov_b32 s21, s30
	ds_read_b128 v[162:165], v217
	ds_read_b128 v[170:173], v213
	ds_read_b128 v[174:177], v213 offset:4096
	ds_read_b128 v[166:169], v217 offset:4096
	s_waitcnt lgkmcnt(6)
	v_mfma_f32_32x32x16_f16 v[2:17], v[186:189], v[194:197], v[2:17]
	v_add_u32_e32 v210, s23, v210
	v_add_u32_e32 v214, s23, v214
	s_waitcnt lgkmcnt(5)
	v_mfma_f32_32x32x16_f16 v[18:33], v[186:189], v[198:201], v[18:33]
	v_add_u32_e32 v211, s23, v211
	v_add_u32_e32 v215, s23, v215
	s_waitcnt lgkmcnt(4)
	v_mfma_f32_32x32x16_f16 v[34:49], v[190:193], v[194:197], v[34:49]
	v_add_u32_e32 v212, s23, v212
	v_add_u32_e32 v216, s23, v216
	v_mfma_f32_32x32x16_f16 v[50:65], v[190:193], v[198:201], v[50:65]
	v_add_u32_e32 v213, s23, v213
	v_add_u32_e32 v217, s23, v217
	s_waitcnt lgkmcnt(0)
	s_waitcnt vmcnt(6)
	s_barrier
	ds_read_b128 v[186:189], v214
	ds_read_b128 v[194:197], v210
	ds_read_b128 v[198:201], v210 offset:4096
	ds_read_b128 v[190:193], v214 offset:4096
	s_add_i32 s28, s20, s22
	s_add_i32 s29, s20, s25
	s_add_i32 m0, s28, 0x0
	v_mfma_f32_32x32x16_f16 v[2:17], v[162:165], v[170:173], v[2:17]
	global_load_lds_dwordx4 v202, s[16:17]
	s_add_i32 m0, s28, 0x400
	v_mfma_f32_32x32x16_f16 v[18:33], v[162:165], v[174:177], v[18:33]
	global_load_lds_dwordx4 v203, s[16:17]
	s_add_i32 m0, s28, 0x800
	v_mfma_f32_32x32x16_f16 v[34:49], v[166:169], v[170:173], v[34:49]
	global_load_lds_dwordx4 v204, s[16:17]
	s_add_i32 m0, s28, 0xc00
	v_mfma_f32_32x32x16_f16 v[50:65], v[166:169], v[174:177], v[50:65]
	global_load_lds_dwordx4 v205, s[16:17]
	ds_read_b128 v[162:165], v215
	ds_read_b128 v[170:173], v211
	ds_read_b128 v[174:177], v211 offset:4096
	ds_read_b128 v[166:169], v215 offset:4096
	s_waitcnt lgkmcnt(6)
	s_add_i32 m0, s29, 0x0
	v_mfma_f32_32x32x16_f16 v[2:17], v[186:189], v[194:197], v[2:17]
	global_load_lds_dwordx4 v208, s[18:19]
	s_waitcnt lgkmcnt(5)
	s_add_i32 m0, s29, 0x400
	v_mfma_f32_32x32x16_f16 v[18:33], v[186:189], v[198:201], v[18:33]
	global_load_lds_dwordx4 v209, s[18:19]
	s_waitcnt lgkmcnt(4)
	v_mfma_f32_32x32x16_f16 v[34:49], v[190:193], v[194:197], v[34:49]
	s_add_u32 s16, s16, 0x80
	s_addc_u32 s17, s17, 0
	v_mfma_f32_32x32x16_f16 v[50:65], v[190:193], v[198:201], v[50:65]
	s_add_u32 s18, s18, 0x80
	s_addc_u32 s19, s19, 0
	ds_read_b128 v[186:189], v216
	ds_read_b128 v[194:197], v212
	ds_read_b128 v[198:201], v212 offset:4096
	ds_read_b128 v[190:193], v216 offset:4096
	s_add_i32 s20, s20, 0xc000
	s_cmp_eq_u32 s20, 0x24000
	s_cselect_b32 s20, 0, s20
	s_waitcnt lgkmcnt(6)
	v_mfma_f32_32x32x16_f16 v[2:17], v[162:165], v[170:173], v[2:17]
	s_add_i32 s30, s21, 0xc000
	s_waitcnt lgkmcnt(5)
	v_mfma_f32_32x32x16_f16 v[18:33], v[162:165], v[174:177], v[18:33]
	s_cmp_eq_u32 s30, 0x24000
	s_waitcnt lgkmcnt(4)
	v_mfma_f32_32x32x16_f16 v[34:49], v[166:169], v[170:173], v[34:49]
	s_cselect_b32 s30, 0, s30
	v_mfma_f32_32x32x16_f16 v[50:65], v[166:169], v[174:177], v[50:65]
	s_sub_i32 s23, s30, s21
	s_mov_b32 s21, s30
	ds_read_b128 v[162:165], v217
	ds_read_b128 v[170:173], v213
	ds_read_b128 v[174:177], v213 offset:4096
	ds_read_b128 v[166:169], v217 offset:4096
	s_waitcnt lgkmcnt(6)
	v_mfma_f32_32x32x16_f16 v[2:17], v[186:189], v[194:197], v[2:17]
	v_add_u32_e32 v210, s23, v210
	v_add_u32_e32 v214, s23, v214
	s_waitcnt lgkmcnt(5)
	v_mfma_f32_32x32x16_f16 v[18:33], v[186:189], v[198:201], v[18:33]
	v_add_u32_e32 v211, s23, v211
	v_add_u32_e32 v215, s23, v215
	s_waitcnt lgkmcnt(4)
	v_mfma_f32_32x32x16_f16 v[34:49], v[190:193], v[194:197], v[34:49]
	v_add_u32_e32 v212, s23, v212
	v_add_u32_e32 v216, s23, v216
	v_mfma_f32_32x32x16_f16 v[50:65], v[190:193], v[198:201], v[50:65]
	v_add_u32_e32 v213, s23, v213
	v_add_u32_e32 v217, s23, v217
	s_waitcnt lgkmcnt(0)
	v_mfma_f32_32x32x16_f16 v[2:17], v[162:165], v[170:173], v[2:17]
	v_mfma_f32_32x32x16_f16 v[18:33], v[162:165], v[174:177], v[18:33]
	v_mfma_f32_32x32x16_f16 v[34:49], v[166:169], v[170:173], v[34:49]
	v_mfma_f32_32x32x16_f16 v[50:65], v[166:169], v[174:177], v[50:65]
	s_nop 15
	v_mul_f32_e32 v2, v218, v2
	v_mul_f32_e32 v3, v218, v3
	v_mul_f32_e32 v4, v218, v4
	v_mul_f32_e32 v5, v218, v5
	v_mul_f32_e32 v6, v218, v6
	v_mul_f32_e32 v7, v218, v7
	v_mul_f32_e32 v8, v218, v8
	v_mul_f32_e32 v9, v218, v9
	v_mul_f32_e32 v2, 0xbfb8aa3b, v2
	v_mul_f32_e32 v3, 0xbfb8aa3b, v3
	v_mul_f32_e32 v4, 0xbfb8aa3b, v4
	v_mul_f32_e32 v5, 0xbfb8aa3b, v5
	v_mul_f32_e32 v6, 0xbfb8aa3b, v6
	v_mul_f32_e32 v7, 0xbfb8aa3b, v7
	v_mul_f32_e32 v8, 0xbfb8aa3b, v8
	v_mul_f32_e32 v9, 0xbfb8aa3b, v9
	v_exp_f32_e32 v2, v2
	v_exp_f32_e32 v3, v3
	v_exp_f32_e32 v4, v4
	v_exp_f32_e32 v5, v5
	v_exp_f32_e32 v6, v6
	v_exp_f32_e32 v7, v7
	v_exp_f32_e32 v8, v8
	v_exp_f32_e32 v9, v9
	v_add_f32_e32 v2, 1.0, v2
	v_add_f32_e32 v3, 1.0, v3
	v_add_f32_e32 v4, 1.0, v4
	v_add_f32_e32 v5, 1.0, v5
	v_add_f32_e32 v6, 1.0, v6
	v_add_f32_e32 v7, 1.0, v7
	v_add_f32_e32 v8, 1.0, v8
	v_add_f32_e32 v9, 1.0, v9
	v_rcp_f32_e32 v2, v2
	v_rcp_f32_e32 v3, v3
	v_rcp_f32_e32 v4, v4
	v_rcp_f32_e32 v5, v5
	v_rcp_f32_e32 v6, v6
	v_rcp_f32_e32 v7, v7
	v_rcp_f32_e32 v8, v8
	v_rcp_f32_e32 v9, v9
	v_cvt_pk_bf16_f32 v130, v2, v3
	v_cvt_pk_bf16_f32 v131, v4, v5
	v_cvt_pk_bf16_f32 v132, v6, v7
	v_cvt_pk_bf16_f32 v133, v8, v9
	v_mul_f32_e32 v10, v218, v10
	v_mul_f32_e32 v11, v218, v11
	v_mul_f32_e32 v12, v218, v12
	v_mul_f32_e32 v13, v218, v13
	v_mul_f32_e32 v14, v218, v14
	v_mul_f32_e32 v15, v218, v15
	v_mul_f32_e32 v16, v218, v16
	v_mul_f32_e32 v17, v218, v17
	v_mul_f32_e32 v10, 0xbfb8aa3b, v10
	v_mul_f32_e32 v11, 0xbfb8aa3b, v11
	v_mul_f32_e32 v12, 0xbfb8aa3b, v12
	v_mul_f32_e32 v13, 0xbfb8aa3b, v13
	v_mul_f32_e32 v14, 0xbfb8aa3b, v14
	v_mul_f32_e32 v15, 0xbfb8aa3b, v15
	v_mul_f32_e32 v16, 0xbfb8aa3b, v16
	v_mul_f32_e32 v17, 0xbfb8aa3b, v17
	v_exp_f32_e32 v10, v10
	v_exp_f32_e32 v11, v11
	v_exp_f32_e32 v12, v12
	v_exp_f32_e32 v13, v13
	v_exp_f32_e32 v14, v14
	v_exp_f32_e32 v15, v15
	v_exp_f32_e32 v16, v16
	v_exp_f32_e32 v17, v17
	v_add_f32_e32 v10, 1.0, v10
	v_add_f32_e32 v11, 1.0, v11
	v_add_f32_e32 v12, 1.0, v12
	v_add_f32_e32 v13, 1.0, v13
	v_add_f32_e32 v14, 1.0, v14
	v_add_f32_e32 v15, 1.0, v15
	v_add_f32_e32 v16, 1.0, v16
	v_add_f32_e32 v17, 1.0, v17
	v_rcp_f32_e32 v10, v10
	v_rcp_f32_e32 v11, v11
	v_rcp_f32_e32 v12, v12
	v_rcp_f32_e32 v13, v13
	v_rcp_f32_e32 v14, v14
	v_rcp_f32_e32 v15, v15
	v_rcp_f32_e32 v16, v16
	v_rcp_f32_e32 v17, v17
	v_cvt_pk_bf16_f32 v134, v10, v11
	v_cvt_pk_bf16_f32 v135, v12, v13
	v_cvt_pk_bf16_f32 v136, v14, v15
	v_cvt_pk_bf16_f32 v137, v16, v17
	v_mul_f32_e32 v18, v219, v18
	v_mul_f32_e32 v19, v219, v19
	v_mul_f32_e32 v20, v219, v20
	v_mul_f32_e32 v21, v219, v21
	v_mul_f32_e32 v22, v219, v22
	v_mul_f32_e32 v23, v219, v23
	v_mul_f32_e32 v24, v219, v24
	v_mul_f32_e32 v25, v219, v25
	v_mul_f32_e32 v18, 0xbfb8aa3b, v18
	v_mul_f32_e32 v19, 0xbfb8aa3b, v19
	v_mul_f32_e32 v20, 0xbfb8aa3b, v20
	v_mul_f32_e32 v21, 0xbfb8aa3b, v21
	v_mul_f32_e32 v22, 0xbfb8aa3b, v22
	v_mul_f32_e32 v23, 0xbfb8aa3b, v23
	v_mul_f32_e32 v24, 0xbfb8aa3b, v24
	v_mul_f32_e32 v25, 0xbfb8aa3b, v25
	v_exp_f32_e32 v18, v18
	v_exp_f32_e32 v19, v19
	v_exp_f32_e32 v20, v20
	v_exp_f32_e32 v21, v21
	v_exp_f32_e32 v22, v22
	v_exp_f32_e32 v23, v23
	v_exp_f32_e32 v24, v24
	v_exp_f32_e32 v25, v25
	v_add_f32_e32 v18, 1.0, v18
	v_add_f32_e32 v19, 1.0, v19
	v_add_f32_e32 v20, 1.0, v20
	v_add_f32_e32 v21, 1.0, v21
	v_add_f32_e32 v22, 1.0, v22
	v_add_f32_e32 v23, 1.0, v23
	v_add_f32_e32 v24, 1.0, v24
	v_add_f32_e32 v25, 1.0, v25
	v_rcp_f32_e32 v18, v18
	v_rcp_f32_e32 v19, v19
	v_rcp_f32_e32 v20, v20
	v_rcp_f32_e32 v21, v21
	v_rcp_f32_e32 v22, v22
	v_rcp_f32_e32 v23, v23
	v_rcp_f32_e32 v24, v24
	v_rcp_f32_e32 v25, v25
	v_cvt_pk_bf16_f32 v138, v18, v19
	v_cvt_pk_bf16_f32 v139, v20, v21
	v_cvt_pk_bf16_f32 v140, v22, v23
	v_cvt_pk_bf16_f32 v141, v24, v25
	v_mul_f32_e32 v26, v219, v26
	v_mul_f32_e32 v27, v219, v27
	v_mul_f32_e32 v28, v219, v28
	v_mul_f32_e32 v29, v219, v29
	v_mul_f32_e32 v30, v219, v30
	v_mul_f32_e32 v31, v219, v31
	v_mul_f32_e32 v32, v219, v32
	v_mul_f32_e32 v33, v219, v33
	v_mul_f32_e32 v26, 0xbfb8aa3b, v26
	v_mul_f32_e32 v27, 0xbfb8aa3b, v27
	v_mul_f32_e32 v28, 0xbfb8aa3b, v28
	v_mul_f32_e32 v29, 0xbfb8aa3b, v29
	v_mul_f32_e32 v30, 0xbfb8aa3b, v30
	v_mul_f32_e32 v31, 0xbfb8aa3b, v31
	v_mul_f32_e32 v32, 0xbfb8aa3b, v32
	v_mul_f32_e32 v33, 0xbfb8aa3b, v33
	v_exp_f32_e32 v26, v26
	v_exp_f32_e32 v27, v27
	v_exp_f32_e32 v28, v28
	v_exp_f32_e32 v29, v29
	v_exp_f32_e32 v30, v30
	v_exp_f32_e32 v31, v31
	v_exp_f32_e32 v32, v32
	v_exp_f32_e32 v33, v33
	v_add_f32_e32 v26, 1.0, v26
	v_add_f32_e32 v27, 1.0, v27
	v_add_f32_e32 v28, 1.0, v28
	v_add_f32_e32 v29, 1.0, v29
	v_add_f32_e32 v30, 1.0, v30
	v_add_f32_e32 v31, 1.0, v31
	v_add_f32_e32 v32, 1.0, v32
	v_add_f32_e32 v33, 1.0, v33
	v_rcp_f32_e32 v26, v26
	v_rcp_f32_e32 v27, v27
	v_rcp_f32_e32 v28, v28
	v_rcp_f32_e32 v29, v29
	v_rcp_f32_e32 v30, v30
	v_rcp_f32_e32 v31, v31
	v_rcp_f32_e32 v32, v32
	v_rcp_f32_e32 v33, v33
	v_cvt_pk_bf16_f32 v142, v26, v27
	v_cvt_pk_bf16_f32 v143, v28, v29
	v_cvt_pk_bf16_f32 v144, v30, v31
	v_cvt_pk_bf16_f32 v145, v32, v33
	v_mul_f32_e32 v34, v218, v34
	v_mul_f32_e32 v35, v218, v35
	v_mul_f32_e32 v36, v218, v36
	v_mul_f32_e32 v37, v218, v37
	v_mul_f32_e32 v38, v218, v38
	v_mul_f32_e32 v39, v218, v39
	v_mul_f32_e32 v40, v218, v40
	v_mul_f32_e32 v41, v218, v41
	v_mul_f32_e32 v34, 0xbfb8aa3b, v34
	v_mul_f32_e32 v35, 0xbfb8aa3b, v35
	v_mul_f32_e32 v36, 0xbfb8aa3b, v36
	v_mul_f32_e32 v37, 0xbfb8aa3b, v37
	v_mul_f32_e32 v38, 0xbfb8aa3b, v38
	v_mul_f32_e32 v39, 0xbfb8aa3b, v39
	v_mul_f32_e32 v40, 0xbfb8aa3b, v40
	v_mul_f32_e32 v41, 0xbfb8aa3b, v41
	v_exp_f32_e32 v34, v34
	v_exp_f32_e32 v35, v35
	v_exp_f32_e32 v36, v36
	v_exp_f32_e32 v37, v37
	v_exp_f32_e32 v38, v38
	v_exp_f32_e32 v39, v39
	v_exp_f32_e32 v40, v40
	v_exp_f32_e32 v41, v41
	v_add_f32_e32 v34, 1.0, v34
	v_add_f32_e32 v35, 1.0, v35
	v_add_f32_e32 v36, 1.0, v36
	v_add_f32_e32 v37, 1.0, v37
	v_add_f32_e32 v38, 1.0, v38
	v_add_f32_e32 v39, 1.0, v39
	v_add_f32_e32 v40, 1.0, v40
	v_add_f32_e32 v41, 1.0, v41
	v_rcp_f32_e32 v34, v34
	v_rcp_f32_e32 v35, v35
	v_rcp_f32_e32 v36, v36
	v_rcp_f32_e32 v37, v37
	v_rcp_f32_e32 v38, v38
	v_rcp_f32_e32 v39, v39
	v_rcp_f32_e32 v40, v40
	v_rcp_f32_e32 v41, v41
	v_cvt_pk_bf16_f32 v146, v34, v35
	v_cvt_pk_bf16_f32 v147, v36, v37
	v_cvt_pk_bf16_f32 v148, v38, v39
	v_cvt_pk_bf16_f32 v149, v40, v41
	v_mul_f32_e32 v42, v218, v42
	v_mul_f32_e32 v43, v218, v43
	v_mul_f32_e32 v44, v218, v44
	v_mul_f32_e32 v45, v218, v45
	v_mul_f32_e32 v46, v218, v46
	v_mul_f32_e32 v47, v218, v47
	v_mul_f32_e32 v48, v218, v48
	v_mul_f32_e32 v49, v218, v49
	v_mul_f32_e32 v42, 0xbfb8aa3b, v42
	v_mul_f32_e32 v43, 0xbfb8aa3b, v43
	v_mul_f32_e32 v44, 0xbfb8aa3b, v44
	v_mul_f32_e32 v45, 0xbfb8aa3b, v45
	v_mul_f32_e32 v46, 0xbfb8aa3b, v46
	v_mul_f32_e32 v47, 0xbfb8aa3b, v47
	v_mul_f32_e32 v48, 0xbfb8aa3b, v48
	v_mul_f32_e32 v49, 0xbfb8aa3b, v49
	v_exp_f32_e32 v42, v42
	v_exp_f32_e32 v43, v43
	v_exp_f32_e32 v44, v44
	v_exp_f32_e32 v45, v45
	v_exp_f32_e32 v46, v46
	v_exp_f32_e32 v47, v47
	v_exp_f32_e32 v48, v48
	v_exp_f32_e32 v49, v49
	v_add_f32_e32 v42, 1.0, v42
	v_add_f32_e32 v43, 1.0, v43
	v_add_f32_e32 v44, 1.0, v44
	v_add_f32_e32 v45, 1.0, v45
	v_add_f32_e32 v46, 1.0, v46
	v_add_f32_e32 v47, 1.0, v47
	v_add_f32_e32 v48, 1.0, v48
	v_add_f32_e32 v49, 1.0, v49
	v_rcp_f32_e32 v42, v42
	v_rcp_f32_e32 v43, v43
	v_rcp_f32_e32 v44, v44
	v_rcp_f32_e32 v45, v45
	v_rcp_f32_e32 v46, v46
	v_rcp_f32_e32 v47, v47
	v_rcp_f32_e32 v48, v48
	v_rcp_f32_e32 v49, v49
	v_cvt_pk_bf16_f32 v150, v42, v43
	v_cvt_pk_bf16_f32 v151, v44, v45
	v_cvt_pk_bf16_f32 v152, v46, v47
	v_cvt_pk_bf16_f32 v153, v48, v49
	v_mul_f32_e32 v50, v219, v50
	v_mul_f32_e32 v51, v219, v51
	v_mul_f32_e32 v52, v219, v52
	v_mul_f32_e32 v53, v219, v53
	v_mul_f32_e32 v54, v219, v54
	v_mul_f32_e32 v55, v219, v55
	v_mul_f32_e32 v56, v219, v56
	v_mul_f32_e32 v57, v219, v57
	v_mul_f32_e32 v50, 0xbfb8aa3b, v50
	v_mul_f32_e32 v51, 0xbfb8aa3b, v51
	v_mul_f32_e32 v52, 0xbfb8aa3b, v52
	v_mul_f32_e32 v53, 0xbfb8aa3b, v53
	v_mul_f32_e32 v54, 0xbfb8aa3b, v54
	v_mul_f32_e32 v55, 0xbfb8aa3b, v55
	v_mul_f32_e32 v56, 0xbfb8aa3b, v56
	v_mul_f32_e32 v57, 0xbfb8aa3b, v57
	v_exp_f32_e32 v50, v50
	v_exp_f32_e32 v51, v51
	v_exp_f32_e32 v52, v52
	v_exp_f32_e32 v53, v53
	v_exp_f32_e32 v54, v54
	v_exp_f32_e32 v55, v55
	v_exp_f32_e32 v56, v56
	v_exp_f32_e32 v57, v57
	v_add_f32_e32 v50, 1.0, v50
	v_add_f32_e32 v51, 1.0, v51
	v_add_f32_e32 v52, 1.0, v52
	v_add_f32_e32 v53, 1.0, v53
	v_add_f32_e32 v54, 1.0, v54
	v_add_f32_e32 v55, 1.0, v55
	v_add_f32_e32 v56, 1.0, v56
	v_add_f32_e32 v57, 1.0, v57
	v_rcp_f32_e32 v50, v50
	v_rcp_f32_e32 v51, v51
	v_rcp_f32_e32 v52, v52
	v_rcp_f32_e32 v53, v53
	v_rcp_f32_e32 v54, v54
	v_rcp_f32_e32 v55, v55
	v_rcp_f32_e32 v56, v56
	v_rcp_f32_e32 v57, v57
	v_cvt_pk_bf16_f32 v154, v50, v51
	v_cvt_pk_bf16_f32 v155, v52, v53
	v_cvt_pk_bf16_f32 v156, v54, v55
	v_cvt_pk_bf16_f32 v157, v56, v57
	v_mul_f32_e32 v58, v219, v58
	v_mul_f32_e32 v59, v219, v59
	v_mul_f32_e32 v60, v219, v60
	v_mul_f32_e32 v61, v219, v61
	v_mul_f32_e32 v62, v219, v62
	v_mul_f32_e32 v63, v219, v63
	v_mul_f32_e32 v64, v219, v64
	v_mul_f32_e32 v65, v219, v65
	v_mul_f32_e32 v58, 0xbfb8aa3b, v58
	v_mul_f32_e32 v59, 0xbfb8aa3b, v59
	v_mul_f32_e32 v60, 0xbfb8aa3b, v60
	v_mul_f32_e32 v61, 0xbfb8aa3b, v61
	v_mul_f32_e32 v62, 0xbfb8aa3b, v62
	v_mul_f32_e32 v63, 0xbfb8aa3b, v63
	v_mul_f32_e32 v64, 0xbfb8aa3b, v64
	v_mul_f32_e32 v65, 0xbfb8aa3b, v65
	v_exp_f32_e32 v58, v58
	v_exp_f32_e32 v59, v59
	v_exp_f32_e32 v60, v60
	v_exp_f32_e32 v61, v61
	v_exp_f32_e32 v62, v62
	v_exp_f32_e32 v63, v63
	v_exp_f32_e32 v64, v64
	v_exp_f32_e32 v65, v65
	v_add_f32_e32 v58, 1.0, v58
	v_add_f32_e32 v59, 1.0, v59
	v_add_f32_e32 v60, 1.0, v60
	v_add_f32_e32 v61, 1.0, v61
	v_add_f32_e32 v62, 1.0, v62
	v_add_f32_e32 v63, 1.0, v63
	v_add_f32_e32 v64, 1.0, v64
	v_add_f32_e32 v65, 1.0, v65
	v_rcp_f32_e32 v58, v58
	v_rcp_f32_e32 v59, v59
	v_rcp_f32_e32 v60, v60
	v_rcp_f32_e32 v61, v61
	v_rcp_f32_e32 v62, v62
	v_rcp_f32_e32 v63, v63
	v_rcp_f32_e32 v64, v64
	v_rcp_f32_e32 v65, v65
	v_cvt_pk_bf16_f32 v158, v58, v59
	v_cvt_pk_bf16_f32 v159, v60, v61
	v_cvt_pk_bf16_f32 v160, v62, v63
	v_cvt_pk_bf16_f32 v161, v64, v65
	s_waitcnt vmcnt(6)
	s_barrier
	ds_read_b128 v[186:189], v214
	ds_read_b128 v[194:197], v210
	ds_read_b128 v[198:201], v210 offset:4096
	ds_read_b128 v[190:193], v214 offset:4096
	s_add_i32 s28, s20, s22
	s_add_i32 s29, s20, s25
	s_add_i32 m0, s28, 0x0
	s_nop 0
	global_load_lds_dwordx4 v202, s[16:17]
	s_add_i32 m0, s28, 0x400
	s_nop 0
	global_load_lds_dwordx4 v203, s[16:17]
	s_add_i32 m0, s28, 0x800
	s_nop 0
	global_load_lds_dwordx4 v204, s[16:17]
	s_add_i32 m0, s28, 0xc00
	s_nop 0
	global_load_lds_dwordx4 v205, s[16:17]
	ds_read_b128 v[162:165], v215
	ds_read_b128 v[170:173], v211
	ds_read_b128 v[174:177], v211 offset:4096
	ds_read_b128 v[166:169], v215 offset:4096
	s_waitcnt lgkmcnt(6)
	s_add_i32 m0, s29, 0x0
	v_mfma_f32_32x32x16_bf16 v[2:17], v[186:189], v[194:197], 0
	global_load_lds_dwordx4 v208, s[18:19]
	s_waitcnt lgkmcnt(5)
	s_add_i32 m0, s29, 0x400
	v_mfma_f32_32x32x16_bf16 v[18:33], v[186:189], v[198:201], 0
	global_load_lds_dwordx4 v209, s[18:19]
	s_waitcnt lgkmcnt(4)
	v_mfma_f32_32x32x16_bf16 v[34:49], v[190:193], v[194:197], 0
	s_add_u32 s16, s16, 0x80
	s_addc_u32 s17, s17, 0
	v_mfma_f32_32x32x16_bf16 v[50:65], v[190:193], v[198:201], 0
	s_add_u32 s18, s18, 0x80
	s_addc_u32 s19, s19, 0
	ds_read_b128 v[186:189], v216
	ds_read_b128 v[194:197], v212
	ds_read_b128 v[198:201], v212 offset:4096
	ds_read_b128 v[190:193], v216 offset:4096
	s_add_i32 s20, s20, 0xc000
	s_cmp_eq_u32 s20, 0x24000
	s_cselect_b32 s20, 0, s20
	s_waitcnt lgkmcnt(6)
	v_mfma_f32_32x32x16_bf16 v[2:17], v[162:165], v[170:173], v[2:17]
	s_add_i32 s30, s21, 0xc000
	s_waitcnt lgkmcnt(5)
	v_mfma_f32_32x32x16_bf16 v[18:33], v[162:165], v[174:177], v[18:33]
	s_cmp_eq_u32 s30, 0x24000
	s_waitcnt lgkmcnt(4)
	v_mfma_f32_32x32x16_bf16 v[34:49], v[166:169], v[170:173], v[34:49]
	s_cselect_b32 s30, 0, s30
	v_mfma_f32_32x32x16_bf16 v[50:65], v[166:169], v[174:177], v[50:65]
	s_sub_i32 s23, s30, s21
	s_mov_b32 s21, s30
	ds_read_b128 v[162:165], v217
	ds_read_b128 v[170:173], v213
	ds_read_b128 v[174:177], v213 offset:4096
	ds_read_b128 v[166:169], v217 offset:4096
	s_waitcnt lgkmcnt(6)
	v_mfma_f32_32x32x16_bf16 v[2:17], v[186:189], v[194:197], v[2:17]
	v_add_u32_e32 v210, s23, v210
	v_add_u32_e32 v214, s23, v214
	s_waitcnt lgkmcnt(5)
	v_mfma_f32_32x32x16_bf16 v[18:33], v[186:189], v[198:201], v[18:33]
	v_add_u32_e32 v211, s23, v211
	v_add_u32_e32 v215, s23, v215
	s_waitcnt lgkmcnt(4)
	v_mfma_f32_32x32x16_bf16 v[34:49], v[190:193], v[194:197], v[34:49]
	v_add_u32_e32 v212, s23, v212
	v_add_u32_e32 v216, s23, v216
	v_mfma_f32_32x32x16_bf16 v[50:65], v[190:193], v[198:201], v[50:65]
	v_add_u32_e32 v213, s23, v213
	v_add_u32_e32 v217, s23, v217
	s_waitcnt lgkmcnt(0)
	s_waitcnt vmcnt(6)
	s_barrier
	ds_read_b128 v[186:189], v214
	ds_read_b128 v[194:197], v210
	ds_read_b128 v[198:201], v210 offset:4096
	ds_read_b128 v[190:193], v214 offset:4096
	s_add_i32 s28, s20, s22
	s_add_i32 s29, s20, s25
	s_add_i32 m0, s28, 0x0
	v_mfma_f32_32x32x16_bf16 v[2:17], v[162:165], v[170:173], v[2:17]
	global_load_lds_dwordx4 v202, s[16:17]
	s_add_i32 m0, s28, 0x400
	v_mfma_f32_32x32x16_bf16 v[18:33], v[162:165], v[174:177], v[18:33]
	global_load_lds_dwordx4 v203, s[16:17]
	s_add_i32 m0, s28, 0x800
	v_mfma_f32_32x32x16_bf16 v[34:49], v[166:169], v[170:173], v[34:49]
	global_load_lds_dwordx4 v204, s[16:17]
	s_add_i32 m0, s28, 0xc00
	v_mfma_f32_32x32x16_bf16 v[50:65], v[166:169], v[174:177], v[50:65]
	global_load_lds_dwordx4 v205, s[16:17]
	ds_read_b128 v[162:165], v215
	ds_read_b128 v[170:173], v211
	ds_read_b128 v[174:177], v211 offset:4096
	ds_read_b128 v[166:169], v215 offset:4096
	s_waitcnt lgkmcnt(6)
	s_add_i32 m0, s29, 0x0
	v_mfma_f32_32x32x16_bf16 v[2:17], v[186:189], v[194:197], v[2:17]
	global_load_lds_dwordx4 v208, s[18:19]
	s_waitcnt lgkmcnt(5)
	s_add_i32 m0, s29, 0x400
	v_mfma_f32_32x32x16_bf16 v[18:33], v[186:189], v[198:201], v[18:33]
	global_load_lds_dwordx4 v209, s[18:19]
	s_waitcnt lgkmcnt(4)
	v_mfma_f32_32x32x16_bf16 v[34:49], v[190:193], v[194:197], v[34:49]
	s_add_u32 s16, s16, 0x80
	s_addc_u32 s17, s17, 0
	v_mfma_f32_32x32x16_bf16 v[50:65], v[190:193], v[198:201], v[50:65]
	s_add_u32 s18, s18, 0x80
	s_addc_u32 s19, s19, 0
	ds_read_b128 v[186:189], v216
	ds_read_b128 v[194:197], v212
	ds_read_b128 v[198:201], v212 offset:4096
	ds_read_b128 v[190:193], v216 offset:4096
	s_add_i32 s20, s20, 0xc000
	s_cmp_eq_u32 s20, 0x24000
	s_cselect_b32 s20, 0, s20
	s_waitcnt lgkmcnt(6)
	v_mfma_f32_32x32x16_bf16 v[2:17], v[162:165], v[170:173], v[2:17]
	s_add_i32 s30, s21, 0xc000
	s_waitcnt lgkmcnt(5)
	v_mfma_f32_32x32x16_bf16 v[18:33], v[162:165], v[174:177], v[18:33]
	s_cmp_eq_u32 s30, 0x24000
	s_waitcnt lgkmcnt(4)
	v_mfma_f32_32x32x16_bf16 v[34:49], v[166:169], v[170:173], v[34:49]
	s_cselect_b32 s30, 0, s30
	v_mfma_f32_32x32x16_bf16 v[50:65], v[166:169], v[174:177], v[50:65]
	s_sub_i32 s23, s30, s21
	s_mov_b32 s21, s30
	ds_read_b128 v[162:165], v217
	ds_read_b128 v[170:173], v213
	ds_read_b128 v[174:177], v213 offset:4096
	ds_read_b128 v[166:169], v217 offset:4096
	s_waitcnt lgkmcnt(6)
	v_mfma_f32_32x32x16_bf16 v[2:17], v[186:189], v[194:197], v[2:17]
	v_add_u32_e32 v210, s23, v210
	v_add_u32_e32 v214, s23, v214
	s_waitcnt lgkmcnt(5)
	v_mfma_f32_32x32x16_bf16 v[18:33], v[186:189], v[198:201], v[18:33]
	v_add_u32_e32 v211, s23, v211
	v_add_u32_e32 v215, s23, v215
	s_waitcnt lgkmcnt(4)
	v_mfma_f32_32x32x16_bf16 v[34:49], v[190:193], v[194:197], v[34:49]
	v_add_u32_e32 v212, s23, v212
	v_add_u32_e32 v216, s23, v216
	v_mfma_f32_32x32x16_bf16 v[50:65], v[190:193], v[198:201], v[50:65]
	v_add_u32_e32 v213, s23, v213
	v_add_u32_e32 v217, s23, v217
	s_waitcnt lgkmcnt(0)
	s_waitcnt vmcnt(6)
	s_barrier
	ds_read_b128 v[186:189], v214
	ds_read_b128 v[194:197], v210
	ds_read_b128 v[198:201], v210 offset:4096
	ds_read_b128 v[190:193], v214 offset:4096
	s_add_i32 s28, s20, s22
	s_add_i32 s29, s20, s25
	s_add_i32 m0, s28, 0x0
	v_mfma_f32_32x32x16_bf16 v[2:17], v[162:165], v[170:173], v[2:17]
	global_load_lds_dwordx4 v202, s[34:35]
	s_add_i32 m0, s28, 0x400
	v_mfma_f32_32x32x16_bf16 v[18:33], v[162:165], v[174:177], v[18:33]
	global_load_lds_dwordx4 v203, s[34:35]
	s_add_i32 m0, s28, 0x800
	v_mfma_f32_32x32x16_bf16 v[34:49], v[166:169], v[170:173], v[34:49]
	global_load_lds_dwordx4 v204, s[34:35]
	s_add_i32 m0, s28, 0xc00
	v_mfma_f32_32x32x16_bf16 v[50:65], v[166:169], v[174:177], v[50:65]
	global_load_lds_dwordx4 v205, s[34:35]
	ds_read_b128 v[162:165], v215
	ds_read_b128 v[170:173], v211
	ds_read_b128 v[174:177], v211 offset:4096
	ds_read_b128 v[166:169], v215 offset:4096
	s_waitcnt lgkmcnt(6)
	s_add_i32 m0, s29, 0x0
	v_mfma_f32_32x32x16_bf16 v[2:17], v[186:189], v[194:197], v[2:17]
	global_load_lds_dwordx4 v206, s[36:37]
	s_waitcnt lgkmcnt(5)
	s_add_i32 m0, s29, 0x400
	v_mfma_f32_32x32x16_bf16 v[18:33], v[186:189], v[198:201], v[18:33]
	global_load_lds_dwordx4 v207, s[36:37]
	s_waitcnt lgkmcnt(4)
	v_mfma_f32_32x32x16_bf16 v[34:49], v[190:193], v[194:197], v[34:49]
	s_add_u32 s34, s34, 0x80
	s_addc_u32 s35, s35, 0
	v_mfma_f32_32x32x16_bf16 v[50:65], v[190:193], v[198:201], v[50:65]
	s_add_u32 s36, s36, 0x80
	s_addc_u32 s37, s37, 0
	ds_read_b128 v[186:189], v216
	ds_read_b128 v[194:197], v212
	ds_read_b128 v[198:201], v212 offset:4096
	ds_read_b128 v[190:193], v216 offset:4096
	s_add_i32 s20, s20, 0xc000
	s_cmp_eq_u32 s20, 0x24000
	s_cselect_b32 s20, 0, s20
	s_waitcnt lgkmcnt(6)
	v_mfma_f32_32x32x16_bf16 v[2:17], v[162:165], v[170:173], v[2:17]
	s_add_i32 s30, s21, 0xc000
	s_waitcnt lgkmcnt(5)
	v_mfma_f32_32x32x16_bf16 v[18:33], v[162:165], v[174:177], v[18:33]
	s_cmp_eq_u32 s30, 0x24000
	s_waitcnt lgkmcnt(4)
	v_mfma_f32_32x32x16_bf16 v[34:49], v[166:169], v[170:173], v[34:49]
	s_cselect_b32 s30, 0, s30
	v_mfma_f32_32x32x16_bf16 v[50:65], v[166:169], v[174:177], v[50:65]
	s_sub_i32 s23, s30, s21
	s_mov_b32 s21, s30
	ds_read_b128 v[162:165], v217
	ds_read_b128 v[170:173], v213
	ds_read_b128 v[174:177], v213 offset:4096
	ds_read_b128 v[166:169], v217 offset:4096
	s_waitcnt lgkmcnt(6)
	v_mfma_f32_32x32x16_bf16 v[2:17], v[186:189], v[194:197], v[2:17]
	v_add_u32_e32 v210, s23, v210
	v_add_u32_e32 v214, s23, v214
	s_waitcnt lgkmcnt(5)
	v_mfma_f32_32x32x16_bf16 v[18:33], v[186:189], v[198:201], v[18:33]
	v_add_u32_e32 v211, s23, v211
	v_add_u32_e32 v215, s23, v215
	s_waitcnt lgkmcnt(4)
	v_mfma_f32_32x32x16_bf16 v[34:49], v[190:193], v[194:197], v[34:49]
	v_add_u32_e32 v212, s23, v212
	v_add_u32_e32 v216, s23, v216
	v_mfma_f32_32x32x16_bf16 v[50:65], v[190:193], v[198:201], v[50:65]
	v_add_u32_e32 v213, s23, v213
	v_add_u32_e32 v217, s23, v217
	s_waitcnt lgkmcnt(0)
	s_waitcnt vmcnt(6)
	s_barrier
	ds_read_b128 v[186:189], v214
	ds_read_b128 v[194:197], v210
	ds_read_b128 v[198:201], v210 offset:4096
	ds_read_b128 v[190:193], v214 offset:4096
	s_add_i32 s28, s20, s22
	s_add_i32 s29, s20, s25
	s_add_i32 m0, s28, 0x0
	v_mfma_f32_32x32x16_bf16 v[2:17], v[162:165], v[170:173], v[2:17]
	global_load_lds_dwordx4 v202, s[34:35]
	s_add_i32 m0, s28, 0x400
	v_mfma_f32_32x32x16_bf16 v[18:33], v[162:165], v[174:177], v[18:33]
	global_load_lds_dwordx4 v203, s[34:35]
	s_add_i32 m0, s28, 0x800
	v_mfma_f32_32x32x16_bf16 v[34:49], v[166:169], v[170:173], v[34:49]
	global_load_lds_dwordx4 v204, s[34:35]
	s_add_i32 m0, s28, 0xc00
	v_mfma_f32_32x32x16_bf16 v[50:65], v[166:169], v[174:177], v[50:65]
	global_load_lds_dwordx4 v205, s[34:35]
	ds_read_b128 v[162:165], v215
	ds_read_b128 v[170:173], v211
	ds_read_b128 v[174:177], v211 offset:4096
	ds_read_b128 v[166:169], v215 offset:4096
	s_waitcnt lgkmcnt(6)
	s_add_i32 m0, s29, 0x0
	v_mfma_f32_32x32x16_bf16 v[2:17], v[186:189], v[194:197], v[2:17]
	global_load_lds_dwordx4 v206, s[36:37]
	s_waitcnt lgkmcnt(5)
	s_add_i32 m0, s29, 0x400
	v_mfma_f32_32x32x16_bf16 v[18:33], v[186:189], v[198:201], v[18:33]
	global_load_lds_dwordx4 v207, s[36:37]
	s_waitcnt lgkmcnt(4)
	v_mfma_f32_32x32x16_bf16 v[34:49], v[190:193], v[194:197], v[34:49]
	s_add_u32 s34, s34, 0x80
	s_addc_u32 s35, s35, 0
	v_mfma_f32_32x32x16_bf16 v[50:65], v[190:193], v[198:201], v[50:65]
	s_add_u32 s36, s36, 0x80
	s_addc_u32 s37, s37, 0
	ds_read_b128 v[186:189], v216
	ds_read_b128 v[194:197], v212
	ds_read_b128 v[198:201], v212 offset:4096
	ds_read_b128 v[190:193], v216 offset:4096
	s_add_i32 s20, s20, 0xc000
	s_cmp_eq_u32 s20, 0x24000
	s_cselect_b32 s20, 0, s20
	s_waitcnt lgkmcnt(6)
	v_mfma_f32_32x32x16_bf16 v[2:17], v[162:165], v[170:173], v[2:17]
	s_add_i32 s30, s21, 0xc000
	s_waitcnt lgkmcnt(5)
	v_mfma_f32_32x32x16_bf16 v[18:33], v[162:165], v[174:177], v[18:33]
	s_cmp_eq_u32 s30, 0x24000
	s_waitcnt lgkmcnt(4)
	v_mfma_f32_32x32x16_bf16 v[34:49], v[166:169], v[170:173], v[34:49]
	s_cselect_b32 s30, 0, s30
	v_mfma_f32_32x32x16_bf16 v[50:65], v[166:169], v[174:177], v[50:65]
	s_sub_i32 s23, s30, s21
	s_mov_b32 s21, s30
	ds_read_b128 v[162:165], v217
	ds_read_b128 v[170:173], v213
	ds_read_b128 v[174:177], v213 offset:4096
	ds_read_b128 v[166:169], v217 offset:4096
	s_waitcnt lgkmcnt(6)
	v_mfma_f32_32x32x16_bf16 v[2:17], v[186:189], v[194:197], v[2:17]
	v_add_u32_e32 v210, s23, v210
	v_add_u32_e32 v214, s23, v214
	s_waitcnt lgkmcnt(5)
	v_mfma_f32_32x32x16_bf16 v[18:33], v[186:189], v[198:201], v[18:33]
	v_add_u32_e32 v211, s23, v211
	v_add_u32_e32 v215, s23, v215
	s_waitcnt lgkmcnt(4)
	v_mfma_f32_32x32x16_bf16 v[34:49], v[190:193], v[194:197], v[34:49]
	v_add_u32_e32 v212, s23, v212
	v_add_u32_e32 v216, s23, v216
	v_mfma_f32_32x32x16_bf16 v[50:65], v[190:193], v[198:201], v[50:65]
	v_add_u32_e32 v213, s23, v213
	v_add_u32_e32 v217, s23, v217
	s_waitcnt lgkmcnt(0)
	v_mfma_f32_32x32x16_bf16 v[2:17], v[162:165], v[170:173], v[2:17]
	v_mfma_f32_32x32x16_bf16 v[18:33], v[162:165], v[174:177], v[18:33]
	v_mfma_f32_32x32x16_bf16 v[34:49], v[166:169], v[170:173], v[34:49]
	v_mfma_f32_32x32x16_bf16 v[50:65], v[166:169], v[174:177], v[50:65]
	s_nop 15
	v_lshlrev_b32_e32 v220, 16, v130
	v_and_b32_e32 v221, 0xffff0000, v130
	v_pk_fma_f32 v[66:67], v[2:3], v[220:221], v[66:67]
	v_lshlrev_b32_e32 v222, 16, v131
	v_and_b32_e32 v223, 0xffff0000, v131
	v_pk_fma_f32 v[68:69], v[4:5], v[222:223], v[68:69]
	v_lshlrev_b32_e32 v224, 16, v132
	v_and_b32_e32 v225, 0xffff0000, v132
	v_pk_fma_f32 v[70:71], v[6:7], v[224:225], v[70:71]
	v_lshlrev_b32_e32 v226, 16, v133
	v_and_b32_e32 v227, 0xffff0000, v133
	v_pk_fma_f32 v[72:73], v[8:9], v[226:227], v[72:73]
	v_lshlrev_b32_e32 v220, 16, v134
	v_and_b32_e32 v221, 0xffff0000, v134
	v_pk_fma_f32 v[74:75], v[10:11], v[220:221], v[74:75]
	v_lshlrev_b32_e32 v222, 16, v135
	v_and_b32_e32 v223, 0xffff0000, v135
	v_pk_fma_f32 v[76:77], v[12:13], v[222:223], v[76:77]
	v_lshlrev_b32_e32 v224, 16, v136
	v_and_b32_e32 v225, 0xffff0000, v136
	v_pk_fma_f32 v[78:79], v[14:15], v[224:225], v[78:79]
	v_lshlrev_b32_e32 v226, 16, v137
	v_and_b32_e32 v227, 0xffff0000, v137
	v_pk_fma_f32 v[80:81], v[16:17], v[226:227], v[80:81]
	v_lshlrev_b32_e32 v220, 16, v138
	v_and_b32_e32 v221, 0xffff0000, v138
	v_pk_fma_f32 v[82:83], v[18:19], v[220:221], v[82:83]
	v_lshlrev_b32_e32 v222, 16, v139
	v_and_b32_e32 v223, 0xffff0000, v139
	v_pk_fma_f32 v[84:85], v[20:21], v[222:223], v[84:85]
	v_lshlrev_b32_e32 v224, 16, v140
	v_and_b32_e32 v225, 0xffff0000, v140
	v_pk_fma_f32 v[86:87], v[22:23], v[224:225], v[86:87]
	v_lshlrev_b32_e32 v226, 16, v141
	v_and_b32_e32 v227, 0xffff0000, v141
	v_pk_fma_f32 v[88:89], v[24:25], v[226:227], v[88:89]
	v_lshlrev_b32_e32 v220, 16, v142
	v_and_b32_e32 v221, 0xffff0000, v142
	v_pk_fma_f32 v[90:91], v[26:27], v[220:221], v[90:91]
	v_lshlrev_b32_e32 v222, 16, v143
	v_and_b32_e32 v223, 0xffff0000, v143
	v_pk_fma_f32 v[92:93], v[28:29], v[222:223], v[92:93]
	v_lshlrev_b32_e32 v224, 16, v144
	v_and_b32_e32 v225, 0xffff0000, v144
	v_pk_fma_f32 v[94:95], v[30:31], v[224:225], v[94:95]
	v_lshlrev_b32_e32 v226, 16, v145
	v_and_b32_e32 v227, 0xffff0000, v145
	v_pk_fma_f32 v[96:97], v[32:33], v[226:227], v[96:97]
	v_lshlrev_b32_e32 v220, 16, v146
	v_and_b32_e32 v221, 0xffff0000, v146
	v_pk_fma_f32 v[98:99], v[34:35], v[220:221], v[98:99]
	v_lshlrev_b32_e32 v222, 16, v147
	v_and_b32_e32 v223, 0xffff0000, v147
	v_pk_fma_f32 v[100:101], v[36:37], v[222:223], v[100:101]
	v_lshlrev_b32_e32 v224, 16, v148
	v_and_b32_e32 v225, 0xffff0000, v148
	v_pk_fma_f32 v[102:103], v[38:39], v[224:225], v[102:103]
	v_lshlrev_b32_e32 v226, 16, v149
	v_and_b32_e32 v227, 0xffff0000, v149
	v_pk_fma_f32 v[104:105], v[40:41], v[226:227], v[104:105]
	v_lshlrev_b32_e32 v220, 16, v150
	v_and_b32_e32 v221, 0xffff0000, v150
	v_pk_fma_f32 v[106:107], v[42:43], v[220:221], v[106:107]
	v_lshlrev_b32_e32 v222, 16, v151
	v_and_b32_e32 v223, 0xffff0000, v151
	v_pk_fma_f32 v[108:109], v[44:45], v[222:223], v[108:109]
	v_lshlrev_b32_e32 v224, 16, v152
	v_and_b32_e32 v225, 0xffff0000, v152
	v_pk_fma_f32 v[110:111], v[46:47], v[224:225], v[110:111]
	v_lshlrev_b32_e32 v226, 16, v153
	v_and_b32_e32 v227, 0xffff0000, v153
	v_pk_fma_f32 v[112:113], v[48:49], v[226:227], v[112:113]
	v_lshlrev_b32_e32 v220, 16, v154
	v_and_b32_e32 v221, 0xffff0000, v154
	v_pk_fma_f32 v[114:115], v[50:51], v[220:221], v[114:115]
	v_lshlrev_b32_e32 v222, 16, v155
	v_and_b32_e32 v223, 0xffff0000, v155
	v_pk_fma_f32 v[116:117], v[52:53], v[222:223], v[116:117]
	v_lshlrev_b32_e32 v224, 16, v156
	v_and_b32_e32 v225, 0xffff0000, v156
	v_pk_fma_f32 v[118:119], v[54:55], v[224:225], v[118:119]
	v_lshlrev_b32_e32 v226, 16, v157
	v_and_b32_e32 v227, 0xffff0000, v157
	v_pk_fma_f32 v[120:121], v[56:57], v[226:227], v[120:121]
	v_lshlrev_b32_e32 v220, 16, v158
	v_and_b32_e32 v221, 0xffff0000, v158
	v_pk_fma_f32 v[122:123], v[58:59], v[220:221], v[122:123]
	v_lshlrev_b32_e32 v222, 16, v159
	v_and_b32_e32 v223, 0xffff0000, v159
	v_pk_fma_f32 v[124:125], v[60:61], v[222:223], v[124:125]
	v_lshlrev_b32_e32 v224, 16, v160
	v_and_b32_e32 v225, 0xffff0000, v160
	v_pk_fma_f32 v[126:127], v[62:63], v[224:225], v[126:127]
	v_lshlrev_b32_e32 v226, 16, v161
	v_and_b32_e32 v227, 0xffff0000, v161
	v_pk_fma_f32 v[128:129], v[64:65], v[226:227], v[128:129]
	s_add_i32 s26, s26, 1
	s_cmp_lg_u32 s26, 4
	s_cbranch_scc1 .Lmg_iloop
	v_cvt_pk_bf16_f32 v220, v66, v67
	v_cvt_pk_bf16_f32 v221, v68, v69
	v_cvt_pk_bf16_f32 v222, v70, v71
	v_cvt_pk_bf16_f32 v223, v72, v73
	s_nop 1
	v_permlane32_swap_b32_e32 v220, v222
	v_permlane32_swap_b32_e32 v221, v223
	global_store_dwordx4 v178, v[220:223], s[42:43] offset:0 sc1
	v_cvt_pk_bf16_f32 v224, v74, v75
	v_cvt_pk_bf16_f32 v225, v76, v77
	v_cvt_pk_bf16_f32 v226, v78, v79
	v_cvt_pk_bf16_f32 v227, v80, v81
	s_nop 1
	v_permlane32_swap_b32_e32 v224, v226
	v_permlane32_swap_b32_e32 v225, v227
	global_store_dwordx4 v178, v[224:227], s[42:43] offset:32 sc1
	v_cvt_pk_bf16_f32 v238, v82, v83
	v_cvt_pk_bf16_f32 v239, v84, v85
	v_cvt_pk_bf16_f32 v240, v86, v87
	v_cvt_pk_bf16_f32 v241, v88, v89
	s_nop 1
	v_permlane32_swap_b32_e32 v238, v240
	v_permlane32_swap_b32_e32 v239, v241
	global_store_dwordx4 v179, v[238:241], s[42:43] offset:0 sc1
	v_cvt_pk_bf16_f32 v242, v90, v91
	v_cvt_pk_bf16_f32 v243, v92, v93
	v_cvt_pk_bf16_f32 v244, v94, v95
	v_cvt_pk_bf16_f32 v245, v96, v97
	s_nop 1
	v_permlane32_swap_b32_e32 v242, v244
	v_permlane32_swap_b32_e32 v243, v245
	global_store_dwordx4 v179, v[242:245], s[42:43] offset:32 sc1
	v_cvt_pk_bf16_f32 v220, v98, v99
	v_cvt_pk_bf16_f32 v221, v100, v101
	v_cvt_pk_bf16_f32 v222, v102, v103
	v_cvt_pk_bf16_f32 v223, v104, v105
	s_nop 1
	v_permlane32_swap_b32_e32 v220, v222
	v_permlane32_swap_b32_e32 v221, v223
	global_store_dwordx4 v178, v[220:223], s[42:43] offset:64 sc1
	v_cvt_pk_bf16_f32 v224, v106, v107
	v_cvt_pk_bf16_f32 v225, v108, v109
	v_cvt_pk_bf16_f32 v226, v110, v111
	v_cvt_pk_bf16_f32 v227, v112, v113
	s_nop 1
	v_permlane32_swap_b32_e32 v224, v226
	v_permlane32_swap_b32_e32 v225, v227
	global_store_dwordx4 v178, v[224:227], s[42:43] offset:96 sc1
	v_cvt_pk_bf16_f32 v238, v114, v115
	v_cvt_pk_bf16_f32 v239, v116, v117
	v_cvt_pk_bf16_f32 v240, v118, v119
	v_cvt_pk_bf16_f32 v241, v120, v121
	s_nop 1
	v_permlane32_swap_b32_e32 v238, v240
	v_permlane32_swap_b32_e32 v239, v241
	global_store_dwordx4 v179, v[238:241], s[42:43] offset:64 sc1
	v_cvt_pk_bf16_f32 v242, v122, v123
	v_cvt_pk_bf16_f32 v243, v124, v125
	v_cvt_pk_bf16_f32 v244, v126, v127
	v_cvt_pk_bf16_f32 v245, v128, v129
	s_nop 1
	v_permlane32_swap_b32_e32 v242, v244
	v_permlane32_swap_b32_e32 v243, v245
	global_store_dwordx4 v179, v[242:245], s[42:43] offset:96 sc1
	s_waitcnt vmcnt(0)
	s_barrier
	s_add_i32 s24, s24, s84
	s_cmpk_gt_i32 s24, 0x1ff
	s_cbranch_scc0 .Lmg_unit
